# x-row conversion and final RMSNorm: loads of a row issued together (were serialised); idle-workgroup conversion items dealt evenly over workgroups
# speedup vs baseline: 1.0581x; 1.0272x over previous
; DI u32x2 pk4(f32x4 v) { u32x2 r; r.x = pk2(v[0], v[1]); r.y = pk2(v[2], v[3]); return r; }
; DI void phase0(CP& p, LAS unsigned char* lds, int wid) {
;     ...
;             const int row = it - NCONV; const f32x4* xr = (const f32x4*)(p.x + (size_t)row * 2048); bf16_t* xb = WSB(OFF_XB) + (size_t)row * 2048;
;             float ss = 0.f;
; #pragma unroll
;             for (int i = 0; i < 8; ++i) { const f32x4 v = __builtin_nontemporal_load(xr + i * 64 + lane); ss += v[0] * v[0] + v[1] * v[1] + v[2] * v[2] + v[3] * v[3]; *(u32x2*)(xb + (i * 64 + lane) * 4) = pk4(v); }
; #pragma unroll
;             for (int o = 1; o < 64; o <<= 1) ss += __shfl_xor(ss, o);
;             if (lane == 0) SSQ(0)[row] = ss;
.LBB0_23:
	s_sub_i32 s40, 0x158f, s89
	s_cmpk_lt_i32 s89, 0x1590
	s_cselect_b32 s84, s40, s89
	s_cmpk_gt_i32 s84, 0x158f
	s_mov_b64 s[70:71], -1
	s_cbranch_scc0 .LBB0_27
	s_add_i32 s40, s84, 0xffffea70
	s_lshl_b64 s[42:43], s[40:41], 13
	s_add_u32 s42, s42, 0x1000
	s_addc_u32 s43, s43, 0
	v_lshl_add_u64 v[44:45], v[2:3], 0, s[42:43]
	s_waitcnt lgkmcnt(0)
	global_load_dwordx4 v[10:13], v[44:45], off offset:-4096 nt
	global_load_dwordx4 v[14:17], v[44:45], off offset:-3072 nt
	global_load_dwordx4 v[18:21], v[44:45], off offset:-2048 nt
	global_load_dwordx4 v[22:25], v[44:45], off offset:-1024 nt
	global_load_dwordx4 v[26:29], v[44:45], off offset:0 nt
	global_load_dwordx4 v[30:33], v[44:45], off offset:1024 nt
	global_load_dwordx4 v[34:37], v[44:45], off offset:2048 nt
	global_load_dwordx4 v[38:41], v[44:45], off offset:3072 nt
	s_lshl_b64 s[42:43], s[40:41], 12
	v_lshl_add_u64 v[42:43], v[6:7], 0, s[42:43]
	s_waitcnt vmcnt(7)
	v_cvt_pk_bf16_f32 v46, v10, v11
	v_cvt_pk_bf16_f32 v47, v12, v13
	global_store_dwordx2 v[42:43], v[46:47], off
	v_mul_f32_e32 v50, v11, v11
	v_fmac_f32_e32 v50, v10, v10
	v_fmac_f32_e32 v50, v12, v12
	v_fmac_f32_e32 v50, v13, v13
	v_mov_b32_e32 v8, v50
	s_waitcnt vmcnt(7)
	v_cvt_pk_bf16_f32 v48, v14, v15
	v_cvt_pk_bf16_f32 v49, v16, v17
	global_store_dwordx2 v[42:43], v[48:49], off offset:512
	v_mul_f32_e32 v50, v15, v15
	v_fmac_f32_e32 v50, v14, v14
	v_fmac_f32_e32 v50, v16, v16
	v_fmac_f32_e32 v50, v17, v17
	v_add_f32_e32 v8, v8, v50
	s_waitcnt vmcnt(7)
	v_cvt_pk_bf16_f32 v46, v18, v19
	v_cvt_pk_bf16_f32 v47, v20, v21
	global_store_dwordx2 v[42:43], v[46:47], off offset:1024
	v_mul_f32_e32 v50, v19, v19
	v_fmac_f32_e32 v50, v18, v18
	v_fmac_f32_e32 v50, v20, v20
	v_fmac_f32_e32 v50, v21, v21
	v_add_f32_e32 v8, v8, v50
	s_waitcnt vmcnt(7)
	v_cvt_pk_bf16_f32 v48, v22, v23
	v_cvt_pk_bf16_f32 v49, v24, v25
	global_store_dwordx2 v[42:43], v[48:49], off offset:1536
	v_mul_f32_e32 v50, v23, v23
	v_fmac_f32_e32 v50, v22, v22
	v_fmac_f32_e32 v50, v24, v24
	v_fmac_f32_e32 v50, v25, v25
	v_add_f32_e32 v8, v8, v50
	s_waitcnt vmcnt(7)
	v_cvt_pk_bf16_f32 v46, v26, v27
	v_cvt_pk_bf16_f32 v47, v28, v29
	global_store_dwordx2 v[42:43], v[46:47], off offset:2048
	v_mul_f32_e32 v50, v27, v27
	v_fmac_f32_e32 v50, v26, v26
	v_fmac_f32_e32 v50, v28, v28
	v_fmac_f32_e32 v50, v29, v29
	v_add_f32_e32 v8, v8, v50
	s_waitcnt vmcnt(7)
	v_cvt_pk_bf16_f32 v48, v30, v31
	v_cvt_pk_bf16_f32 v49, v32, v33
	global_store_dwordx2 v[42:43], v[48:49], off offset:2560
	v_mul_f32_e32 v50, v31, v31
	v_fmac_f32_e32 v50, v30, v30
	v_fmac_f32_e32 v50, v32, v32
	v_fmac_f32_e32 v50, v33, v33
	v_add_f32_e32 v8, v8, v50
	s_waitcnt vmcnt(7)
	v_cvt_pk_bf16_f32 v46, v34, v35
	v_cvt_pk_bf16_f32 v47, v36, v37
	global_store_dwordx2 v[42:43], v[46:47], off offset:3072
	v_mul_f32_e32 v50, v35, v35
	v_fmac_f32_e32 v50, v34, v34
	v_fmac_f32_e32 v50, v36, v36
	v_fmac_f32_e32 v50, v37, v37
	v_add_f32_e32 v8, v8, v50
	s_waitcnt vmcnt(7)
	v_cvt_pk_bf16_f32 v48, v38, v39
	v_cvt_pk_bf16_f32 v49, v40, v41
	global_store_dwordx2 v[42:43], v[48:49], off offset:3584
	v_mul_f32_e32 v50, v39, v39
	v_fmac_f32_e32 v50, v38, v38
	v_fmac_f32_e32 v50, v40, v40
	v_fmac_f32_e32 v50, v41, v41
	v_add_f32_e32 v8, v8, v50
	ds_bpermute_b32 v10, v224, v8
	s_waitcnt lgkmcnt(0)
	v_add_f32_e32 v8, v8, v10
	ds_bpermute_b32 v10, v225, v8
	s_waitcnt lgkmcnt(0)
	v_add_f32_e32 v8, v8, v10
	ds_bpermute_b32 v10, v226, v8
	s_waitcnt lgkmcnt(0)
	v_add_f32_e32 v8, v8, v10
	ds_bpermute_b32 v10, v227, v8
	s_waitcnt lgkmcnt(0)
	v_add_f32_e32 v8, v8, v10
	ds_bpermute_b32 v10, v228, v8
	s_waitcnt lgkmcnt(0)
	v_add_f32_e32 v8, v8, v10
	ds_bpermute_b32 v10, v229, v8
	s_and_saveexec_b64 s[70:71], s[2:3]
	s_cbranch_execz .LBB0_26
	s_lshl_b64 s[42:43], s[40:41], 2
	s_add_u32 s42, s91, s42
	s_addc_u32 s43, s92, s43
	s_waitcnt lgkmcnt(0)
	v_add_f32_e32 v8, v8, v10
	global_store_dword v9, v8, s[42:43]

; DI void phase0(CP& p, LAS unsigned char* lds, int wid) {
;     ...
;     const int gw = blockIdx.x * 8 + wid, nw = gridDim.x * 8;
;     for (int it0 = gw; it0 < NCONV + NXROW; it0 += nw) {
.LBB0_398:
	s_and_b64 vcc, exec, s[8:9]
	s_cbranch_vccz .Lconv_skip_0
	s_cmpk_eq_i32 s7, 0x100
	s_cbranch_scc0 .Lconv_skip_0
	s_and_b32 s12, s6, 31
	s_lshl_b32 s12, s12, 3
	s_lshr_b32 s13, s6, 5
	s_or_b32 s12, s12, s13
	s_cmpk_lt_u32 s12, 128
	s_cbranch_scc1 .Lconv_skip_0
	s_and_b32 s12, s6, 31
	s_lshl_b32 s12, s12, 3
	s_lshr_b32 s13, s6, 5
	s_or_b32 s12, s12, s13
	s_addk_i32 s12, -128
	s_mul_i32 s13, s33, 128
	s_add_i32 s12, s12, s13
	s_add_i32 s99, s12, 3472
	s_movk_i32 s101, 5135
	s_movk_i32 s100, 1024
	s_mov_b32 s98, 1
	s_branch .Lconv_entry
.Lconv_ret_1:
	s_and_b32 s12, s6, 31
	s_lshl_b32 s12, s12, 3
	s_lshr_b32 s13, s6, 5
	s_or_b32 s12, s12, s13
	s_addk_i32 s12, -128
	s_mul_i32 s13, s33, 128
	s_add_i32 s12, s12, s13
	s_sub_i32 s12, 1023, s12
	s_add_i32 s99, s12, 2752
	s_movk_i32 s101, 2767
	s_movk_i32 s100, 16384
	s_mov_b32 s98, 2
	s_branch .Lconv_entry

; DI void phase0(CP& p, LAS unsigned char* lds, int wid) {
;     ...
;     for (int it0 = gw; it0 < NCONV + NXROW; it0 += nw) {
;         const int it = it0 < NCONV ? NCONV - 1 - it0 : it0;
;         if (it < NCONV) {
;             const float* src; const float* src2 = nullptr; const float* gain = nullptr; bf16_t* dst; int ld, K, mode = CM_ID, coff = 0, t0;
;             if (it < 256) { src = p.w_in_ab; gain = p.g_mix; dst = WSB(OFF_W1UZ); ld = 3072; K = 2048; mode = CM_UZ; t0 = 0; }
;             else if (it < 384) { src = p.w_in_ab; gain = p.g_mix; dst = WSB(OFF_W1V); ld = 3072; K = 2048; coff = 1024; t0 = 256; }
;             else if (it < 640) { src = p.w_out_ab; dst = WSB(OFF_WOAB); ld = 2048; K = 2048; mode = CM_P32; t0 = 384; }
;             else if (it < 2048) { src = p.w_gate; src2 = p.w_up; gain = p.g_ffn; dst = WSB(OFF_WGU0); ld = DFF; K = 2048; mode = CM_GU; t0 = 640; }
;             else if (it < 2752) { src = p.w_down; dst = WSB(OFF_WD0); ld = 2048; K = DFF; mode = CM_P32; t0 = 2048; }
;             else if (it < 2768) { src = p.w_pool; dst = WSB(OFF_WPOOL); ld = 256; K = 256; mode = CM_POOL; t0 = 2752; }
;             else if (it < 2928) { src = p.w_in_c; gain = p.g_mix + 2048; dst = WSB(OFF_WINC); ld = 1088; K = 2048; mode = CM_INC; t0 = 2768; }
;             else if (it < 3024) { src = p.w_uq; gain = p.g_cq; dst = WSB(OFF_WUQ); ld = 3072; K = 512; mode = CM_UQ; t0 = 2928; }
;             else if (it < 3088) { src = p.w_ukv; gain = p.g_ckv; dst = WSB(OFF_WUKK); ld = 4096; K = 512; mode = CM_UKVK; t0 = 3024; }
;             else if (it < 3152) { src = p.w_ukv; gain = p.g_ckv; dst = WSB(OFF_WUKV); ld = 4096; K = 512; mode = CM_UKVV; t0 = 3088; }
;             else if (it < 3408) { src = p.w_out_c; dst = WSB(OFF_WOC); ld = 2048; K = 2048; mode = CM_P32; t0 = 3152; }
;             else if (it < 4816) { src = p.w_gate + (size_t)2048 * DFF; src2 = p.w_up + (size_t)2048 * DFF; gain = p.g_ffn + 2048; dst = WSB(OFF_WGU1); ld = DFF; K = 2048; mode = CM_GU; t0 = 3408; }
;             else { src = p.w_down + (size_t)DFF * 2048; dst = WSB(OFF_WD1); ld = 2048; K = DFF; mode = CM_P32; t0 = 4816; }
;             conv_item(lane, lds + wid * 9216, src, src2, gain, dst, ld, K, mode, coff, it - t0);
.LBB0_710:
	s_and_b64 vcc, exec, s[4:5]
	s_cbranch_vccz .Lconv_skip_1
	s_cmpk_eq_i32 s7, 0x100
	s_cbranch_scc0 .Lconv_skip_1
	s_and_b32 s12, s6, 31
	s_lshl_b32 s12, s12, 3
	s_lshr_b32 s13, s6, 5
	s_or_b32 s12, s12, s13
	s_cmpk_lt_u32 s12, 128
	s_cbranch_scc1 .Lconv_skip_1
	s_and_b32 s12, s6, 31
	s_lshl_b32 s12, s12, 3
	s_lshr_b32 s13, s6, 5
	s_or_b32 s12, s12, s13
	s_addk_i32 s12, -128
	s_mul_i32 s13, s33, 128
	s_add_i32 s12, s12, s13
	s_add_i32 s99, s12, 2368
	s_movk_i32 s101, 3471
	s_movk_i32 s100, 1024
	s_mov_b32 s98, 3
	s_branch .Lconv_entry

; DI void phase0(CP& p, LAS unsigned char* lds, int wid) {
;     ...
;     for (int it0 = gw; it0 < NCONV + NXROW; it0 += nw) {
;         const int it = it0 < NCONV ? NCONV - 1 - it0 : it0;
;         if (it < NCONV) {
;             const float* src; const float* src2 = nullptr; const float* gain = nullptr; bf16_t* dst; int ld, K, mode = CM_ID, coff = 0, t0;
;             if (it < 256) { src = p.w_in_ab; gain = p.g_mix; dst = WSB(OFF_W1UZ); ld = 3072; K = 2048; mode = CM_UZ; t0 = 0; }
;             else if (it < 384) { src = p.w_in_ab; gain = p.g_mix; dst = WSB(OFF_W1V); ld = 3072; K = 2048; coff = 1024; t0 = 256; }
;             else if (it < 640) { src = p.w_out_ab; dst = WSB(OFF_WOAB); ld = 2048; K = 2048; mode = CM_P32; t0 = 384; }
;             else if (it < 2048) { src = p.w_gate; src2 = p.w_up; gain = p.g_ffn; dst = WSB(OFF_WGU0); ld = DFF; K = 2048; mode = CM_GU; t0 = 640; }
;             else if (it < 2752) { src = p.w_down; dst = WSB(OFF_WD0); ld = 2048; K = DFF; mode = CM_P32; t0 = 2048; }
;             else if (it < 2768) { src = p.w_pool; dst = WSB(OFF_WPOOL); ld = 256; K = 256; mode = CM_POOL; t0 = 2752; }
;             else if (it < 2928) { src = p.w_in_c; gain = p.g_mix + 2048; dst = WSB(OFF_WINC); ld = 1088; K = 2048; mode = CM_INC; t0 = 2768; }
;             else if (it < 3024) { src = p.w_uq; gain = p.g_cq; dst = WSB(OFF_WUQ); ld = 3072; K = 512; mode = CM_UQ; t0 = 2928; }
;             else if (it < 3088) { src = p.w_ukv; gain = p.g_ckv; dst = WSB(OFF_WUKK); ld = 4096; K = 512; mode = CM_UKVK; t0 = 3024; }
;             else if (it < 3152) { src = p.w_ukv; gain = p.g_ckv; dst = WSB(OFF_WUKV); ld = 4096; K = 512; mode = CM_UKVV; t0 = 3088; }
;             else if (it < 3408) { src = p.w_out_c; dst = WSB(OFF_WOC); ld = 2048; K = 2048; mode = CM_P32; t0 = 3152; }
;             else if (it < 4816) { src = p.w_gate + (size_t)2048 * DFF; src2 = p.w_up + (size_t)2048 * DFF; gain = p.g_ffn + 2048; dst = WSB(OFF_WGU1); ld = DFF; K = 2048; mode = CM_GU; t0 = 3408; }
;             else { src = p.w_down + (size_t)DFF * 2048; dst = WSB(OFF_WD1); ld = 2048; K = DFF; mode = CM_P32; t0 = 4816; }
;             conv_item(lane, lds + wid * 9216, src, src2, gain, dst, ld, K, mode, coff, it - t0);
.LBB0_898:
	s_and_b64 vcc, exec, s[8:9]
	s_cbranch_vccz .Lconv_skip_2
	s_cmpk_eq_i32 s7, 0x100
	s_cbranch_scc0 .Lconv_skip_2
	s_and_b32 s12, s6, 31
	s_lshl_b32 s12, s12, 3
	s_lshr_b32 s13, s6, 5
	s_or_b32 s12, s12, s13
	s_cmpk_lt_u32 s12, 160
	s_cbranch_scc1 .Lconv_skip_2
	s_and_b32 s12, s6, 31
	s_lshl_b32 s12, s12, 3
	s_lshr_b32 s13, s6, 5
	s_or_b32 s12, s12, s13
	s_addk_i32 s12, -160
	s_mul_i32 s13, s33, 96
	s_add_i32 s12, s12, s13
	s_add_i32 s99, s12, 832
	s_movk_i32 s101, 2367
	s_movk_i32 s100, 768
	s_mov_b32 s98, 4
	s_branch .Lconv_tin

; DI void phase0(CP& p, LAS unsigned char* lds, int wid) {
;     ...
;     for (int it0 = gw; it0 < NCONV + NXROW; it0 += nw) {
;         const int it = it0 < NCONV ? NCONV - 1 - it0 : it0;
;         if (it < NCONV) {
;             const float* src; const float* src2 = nullptr; const float* gain = nullptr; bf16_t* dst; int ld, K, mode = CM_ID, coff = 0, t0;
;             if (it < 256) { src = p.w_in_ab; gain = p.g_mix; dst = WSB(OFF_W1UZ); ld = 3072; K = 2048; mode = CM_UZ; t0 = 0; }
;             else if (it < 384) { src = p.w_in_ab; gain = p.g_mix; dst = WSB(OFF_W1V); ld = 3072; K = 2048; coff = 1024; t0 = 256; }
;             else if (it < 640) { src = p.w_out_ab; dst = WSB(OFF_WOAB); ld = 2048; K = 2048; mode = CM_P32; t0 = 384; }
;             else if (it < 2048) { src = p.w_gate; src2 = p.w_up; gain = p.g_ffn; dst = WSB(OFF_WGU0); ld = DFF; K = 2048; mode = CM_GU; t0 = 640; }
;             else if (it < 2752) { src = p.w_down; dst = WSB(OFF_WD0); ld = 2048; K = DFF; mode = CM_P32; t0 = 2048; }
;             else if (it < 2768) { src = p.w_pool; dst = WSB(OFF_WPOOL); ld = 256; K = 256; mode = CM_POOL; t0 = 2752; }
;             else if (it < 2928) { src = p.w_in_c; gain = p.g_mix + 2048; dst = WSB(OFF_WINC); ld = 1088; K = 2048; mode = CM_INC; t0 = 2768; }
;             else if (it < 3024) { src = p.w_uq; gain = p.g_cq; dst = WSB(OFF_WUQ); ld = 3072; K = 512; mode = CM_UQ; t0 = 2928; }
;             else if (it < 3088) { src = p.w_ukv; gain = p.g_ckv; dst = WSB(OFF_WUKK); ld = 4096; K = 512; mode = CM_UKVK; t0 = 3024; }
;             else if (it < 3152) { src = p.w_ukv; gain = p.g_ckv; dst = WSB(OFF_WUKV); ld = 4096; K = 512; mode = CM_UKVV; t0 = 3088; }
;             else if (it < 3408) { src = p.w_out_c; dst = WSB(OFF_WOC); ld = 2048; K = 2048; mode = CM_P32; t0 = 3152; }
;             else if (it < 4816) { src = p.w_gate + (size_t)2048 * DFF; src2 = p.w_up + (size_t)2048 * DFF; gain = p.g_ffn + 2048; dst = WSB(OFF_WGU1); ld = DFF; K = 2048; mode = CM_GU; t0 = 3408; }
;             else { src = p.w_down + (size_t)DFF * 2048; dst = WSB(OFF_WD1); ld = 2048; K = DFF; mode = CM_P32; t0 = 4816; }
;             conv_item(lane, lds + wid * 9216, src, src2, gain, dst, ld, K, mode, coff, it - t0);
.LBB0_1017:
	s_and_b64 vcc, exec, s[2:3]
	s_cbranch_vccz .Lconv_skip_3
	s_cmpk_eq_i32 s7, 0x100
	s_cbranch_scc0 .Lconv_skip_3
	s_and_b32 s12, s6, 31
	s_lshl_b32 s12, s12, 3
	s_lshr_b32 s13, s6, 5
	s_or_b32 s12, s12, s13
	s_cmpk_lt_u32 s12, 128
	s_cbranch_scc1 .Lconv_skip_3
	s_and_b32 s12, s6, 31
	s_lshl_b32 s12, s12, 3
	s_lshr_b32 s13, s6, 5
	s_or_b32 s12, s12, s13
	s_addk_i32 s12, -128
	s_mul_i32 s13, s33, 128
	s_add_i32 s12, s12, s13
	s_add_i32 s99, s12, 704
	s_movk_i32 s101, 831
	s_movk_i32 s100, 16384
	s_mov_b32 s98, 5
	s_branch .Lconv_tin

; DI void phase0(CP& p, LAS unsigned char* lds, int wid) {
;     ...
;     for (int it0 = gw; it0 < NCONV + NXROW; it0 += nw) {
;         const int it = it0 < NCONV ? NCONV - 1 - it0 : it0;
;         if (it < NCONV) {
;             const float* src; const float* src2 = nullptr; const float* gain = nullptr; bf16_t* dst; int ld, K, mode = CM_ID, coff = 0, t0;
;             if (it < 256) { src = p.w_in_ab; gain = p.g_mix; dst = WSB(OFF_W1UZ); ld = 3072; K = 2048; mode = CM_UZ; t0 = 0; }
;             else if (it < 384) { src = p.w_in_ab; gain = p.g_mix; dst = WSB(OFF_W1V); ld = 3072; K = 2048; coff = 1024; t0 = 256; }
;             else if (it < 640) { src = p.w_out_ab; dst = WSB(OFF_WOAB); ld = 2048; K = 2048; mode = CM_P32; t0 = 384; }
;             else if (it < 2048) { src = p.w_gate; src2 = p.w_up; gain = p.g_ffn; dst = WSB(OFF_WGU0); ld = DFF; K = 2048; mode = CM_GU; t0 = 640; }
;             else if (it < 2752) { src = p.w_down; dst = WSB(OFF_WD0); ld = 2048; K = DFF; mode = CM_P32; t0 = 2048; }
;             else if (it < 2768) { src = p.w_pool; dst = WSB(OFF_WPOOL); ld = 256; K = 256; mode = CM_POOL; t0 = 2752; }
;             else if (it < 2928) { src = p.w_in_c; gain = p.g_mix + 2048; dst = WSB(OFF_WINC); ld = 1088; K = 2048; mode = CM_INC; t0 = 2768; }
;             else if (it < 3024) { src = p.w_uq; gain = p.g_cq; dst = WSB(OFF_WUQ); ld = 3072; K = 512; mode = CM_UQ; t0 = 2928; }
;             else if (it < 3088) { src = p.w_ukv; gain = p.g_ckv; dst = WSB(OFF_WUKK); ld = 4096; K = 512; mode = CM_UKVK; t0 = 3024; }
;             else if (it < 3152) { src = p.w_ukv; gain = p.g_ckv; dst = WSB(OFF_WUKV); ld = 4096; K = 512; mode = CM_UKVV; t0 = 3088; }
;             else if (it < 3408) { src = p.w_out_c; dst = WSB(OFF_WOC); ld = 2048; K = 2048; mode = CM_P32; t0 = 3152; }
;             else if (it < 4816) { src = p.w_gate + (size_t)2048 * DFF; src2 = p.w_up + (size_t)2048 * DFF; gain = p.g_ffn + 2048; dst = WSB(OFF_WGU1); ld = DFF; K = 2048; mode = CM_GU; t0 = 3408; }
;             else { src = p.w_down + (size_t)DFF * 2048; dst = WSB(OFF_WD1); ld = 2048; K = DFF; mode = CM_P32; t0 = 4816; }
;             conv_item(lane, lds + wid * 9216, src, src2, gain, dst, ld, K, mode, coff, it - t0);
.LBB0_1265:
	s_and_b64 vcc, exec, s[4:5]
	s_cbranch_vccz .Lconv_skip_4
	s_cmpk_eq_i32 s7, 0x100
	s_cbranch_scc0 .Lconv_skip_4
	s_and_b32 s12, s6, 31
	s_lshl_b32 s12, s12, 3
	s_lshr_b32 s13, s6, 5
	s_or_b32 s12, s12, s13
	s_cmpk_lt_u32 s12, 128
	s_cbranch_scc1 .Lconv_skip_4
	s_and_b32 s12, s6, 31
	s_lshl_b32 s12, s12, 3
	s_lshr_b32 s13, s6, 5
	s_or_b32 s12, s12, s13
	s_addk_i32 s12, -128
	s_mul_i32 s13, s33, 128
	s_add_i32 s12, s12, s13
	s_add_i32 s99, s12, 0
	s_movk_i32 s101, 703
	s_movk_i32 s100, 16384
	s_mov_b32 s98, 6
	s_branch .Lconv_tin

; DI float bf_lo(unsigned w) { return __uint_as_float(w << 16); }
; DI float bf_hi(unsigned w) { return __uint_as_float(w & 0xffff0000u); }
; DI float rstd_of(float ssq, float inv_n) { return __builtin_amdgcn_rsqf(ssq * inv_n + 1e-6f); }
; DI int lane_id() { int l = __builtin_amdgcn_mbcnt_hi(-1, __builtin_amdgcn_mbcnt_lo(-1, 0)); asm volatile("" : "+v"(l)); return l; }
; DI void phase_final(CP& p, int wid) {
;     const int lane = lane_id();
;     for (int it = blockIdx.x; it < 1024; it += gridDim.x) {
;         const int row = it * 8 + wid; const float rs = rstd_of(SSQ(7)[row], 1.f / 2048.f);
;         const u32x4* xr = (const u32x4*)(WSB(OFF_XB) + (size_t)row * 2048); f32x4* orow = (f32x4*)(p.out + (size_t)row * 2048); const f32x4* gf = (const f32x4*)p.g_final;
; #pragma unroll
;         for (int i = 0; i < 4; ++i) { const u32x4 w = xr[i * 64 + lane]; const int c = (i * 64 + lane) * 2;
;             const f32x4 a = {bf_lo(w.x), bf_hi(w.x), bf_lo(w.y), bf_hi(w.y)}, b = {bf_lo(w.z), bf_hi(w.z), bf_lo(w.w), bf_hi(w.w)};
;             orow[c] = a * rs * gf[c]; orow[c + 1] = b * rs * gf[c + 1]; }
;     }
; }
.LBB0_1416:
	s_cmp_lt_i32 s34, 14
	s_cselect_b64 s[4:5], -1, 0
	s_and_b64 s[2:3], s[4:5], s[2:3]
	s_andn2_b64 vcc, exec, s[2:3]
	s_cbranch_vccnz .LBB0_1420
	v_mbcnt_hi_u32_b32 v16, -1, v254
	s_cmpk_gt_i32 s6, 0x3ff
	s_cbranch_scc1 .LBB0_1420
	s_load_dwordx4 s[8:11], s[0:1], 0xa0
	s_load_dwordx2 s[2:3], s[0:1], 0x18
	v_ashrrev_i32_e32 v17, 31, v16
	v_lshlrev_b32_e32 v0, 1, v16
	v_add_u32_e32 v4, 0x80, v0
	s_waitcnt lgkmcnt(0)
	s_add_u32 s4, s10, 0xcd38000
	v_add_u32_e32 v8, 0x100, v0
	v_add_u32_e32 v12, 0x180, v0
	v_lshl_add_u64 v[16:17], v[16:17], 4, s[10:11]
	s_mov_b64 s[0:1], 0xad00000
	v_ashrrev_i32_e32 v1, 31, v0
	s_addc_u32 s5, s11, 0
	v_ashrrev_i32_e32 v5, 31, v4
	v_ashrrev_i32_e32 v9, 31, v8
	v_ashrrev_i32_e32 v13, 31, v12
	v_lshl_add_u64 v[16:17], v[16:17], 0, s[0:1]
	s_lshl_b32 s0, s6, 3
	v_lshl_add_u64 v[2:3], v[0:1], 4, s[2:3]
	v_lshl_add_u64 v[6:7], v[4:5], 4, s[2:3]
	v_lshl_add_u64 v[10:11], v[8:9], 4, s[2:3]
	v_lshl_add_u64 v[14:15], v[12:13], 4, s[2:3]
	s_add_i32 s0, s33, s0
	s_lshl_b32 s10, s7, 3
	v_mov_b32_e32 v18, 0
	v_mov_b32_e32 v19, 0x358637bd
	global_load_dwordx4 v[40:43], v[2:3], off
	global_load_dwordx4 v[44:47], v[2:3], off offset:16
	global_load_dwordx4 v[48:51], v[6:7], off
	global_load_dwordx4 v[52:55], v[6:7], off offset:16
	global_load_dwordx4 v[56:59], v[10:11], off
	global_load_dwordx4 v[60:63], v[10:11], off offset:16
	global_load_dwordx4 v[64:67], v[14:15], off
	global_load_dwordx4 v[68:71], v[14:15], off offset:16
	s_waitcnt vmcnt(0)
.LBB0_1419:
	s_ashr_i32 s1, s0, 31
	s_lshl_b64 s[2:3], s[0:1], 2
	s_add_u32 s2, s4, s2
	s_addc_u32 s3, s5, s3
	global_load_dword v32, v18, s[2:3]
	s_lshl_b64 s[2:3], s[0:1], 13
	s_add_u32 s2, s8, s2
	s_addc_u32 s3, s9, s3
	s_lshl_b64 s[12:13], s[0:1], 12
	v_lshl_add_u64 v[28:29], v[16:17], 0, s[12:13]
	global_load_dwordx4 v[20:23], v[28:29], off
	global_load_dwordx4 v[72:75], v[28:29], off offset:1024
	global_load_dwordx4 v[76:79], v[28:29], off offset:2048
	global_load_dwordx4 v[80:83], v[28:29], off offset:3072
	s_add_i32 s6, s6, s7
	s_add_i32 s0, s0, s10
	s_waitcnt vmcnt(4)
	v_fmamk_f32 v32, v32, 0x3a000000, v19
	v_rsq_f32_e32 v32, v32
	v_lshl_add_u64 v[30:31], v[0:1], 4, s[2:3]
	s_waitcnt vmcnt(3)
	v_lshlrev_b32_e32 v34, 16, v20
	v_and_b32_e32 v35, 0xffff0000, v20
	v_lshlrev_b32_e32 v36, 16, v21
	v_and_b32_e32 v37, 0xffff0000, v21
	v_pk_mul_f32 v[34:35], v[32:33], v[34:35] op_sel_hi:[0,1]
	v_pk_mul_f32 v[36:37], v[32:33], v[36:37] op_sel_hi:[0,1]
	v_pk_mul_f32 v[84:85], v[40:41], v[34:35]
	v_pk_mul_f32 v[86:87], v[42:43], v[36:37]
	global_store_dwordx4 v[30:31], v[84:87], off
	v_lshlrev_b32_e32 v34, 16, v22
	v_and_b32_e32 v35, 0xffff0000, v22
	v_lshlrev_b32_e32 v36, 16, v23
	v_and_b32_e32 v37, 0xffff0000, v23
	v_pk_mul_f32 v[34:35], v[32:33], v[34:35] op_sel_hi:[0,1]
	v_pk_mul_f32 v[36:37], v[32:33], v[36:37] op_sel_hi:[0,1]
	v_pk_mul_f32 v[88:89], v[44:45], v[34:35]
	v_pk_mul_f32 v[90:91], v[46:47], v[36:37]
	global_store_dwordx4 v[30:31], v[88:91], off offset:16
	v_lshl_add_u64 v[30:31], v[4:5], 4, s[2:3]
	s_waitcnt vmcnt(4)
	v_lshlrev_b32_e32 v34, 16, v72
	v_and_b32_e32 v35, 0xffff0000, v72
	v_lshlrev_b32_e32 v36, 16, v73
	v_and_b32_e32 v37, 0xffff0000, v73
	v_pk_mul_f32 v[34:35], v[32:33], v[34:35] op_sel_hi:[0,1]
	v_pk_mul_f32 v[36:37], v[32:33], v[36:37] op_sel_hi:[0,1]
	v_pk_mul_f32 v[84:85], v[48:49], v[34:35]
	v_pk_mul_f32 v[86:87], v[50:51], v[36:37]
	global_store_dwordx4 v[30:31], v[84:87], off
	v_lshlrev_b32_e32 v34, 16, v74
	v_and_b32_e32 v35, 0xffff0000, v74
	v_lshlrev_b32_e32 v36, 16, v75
	v_and_b32_e32 v37, 0xffff0000, v75
	v_pk_mul_f32 v[34:35], v[32:33], v[34:35] op_sel_hi:[0,1]
	v_pk_mul_f32 v[36:37], v[32:33], v[36:37] op_sel_hi:[0,1]
	v_pk_mul_f32 v[88:89], v[52:53], v[34:35]
	v_pk_mul_f32 v[90:91], v[54:55], v[36:37]
	global_store_dwordx4 v[30:31], v[88:91], off offset:16
	v_lshl_add_u64 v[30:31], v[8:9], 4, s[2:3]
	s_waitcnt vmcnt(5)
	v_lshlrev_b32_e32 v34, 16, v76
	v_and_b32_e32 v35, 0xffff0000, v76
	v_lshlrev_b32_e32 v36, 16, v77
	v_and_b32_e32 v37, 0xffff0000, v77
	v_pk_mul_f32 v[34:35], v[32:33], v[34:35] op_sel_hi:[0,1]
	v_pk_mul_f32 v[36:37], v[32:33], v[36:37] op_sel_hi:[0,1]
	v_pk_mul_f32 v[84:85], v[56:57], v[34:35]
	v_pk_mul_f32 v[86:87], v[58:59], v[36:37]
	global_store_dwordx4 v[30:31], v[84:87], off
	v_lshlrev_b32_e32 v34, 16, v78
	v_and_b32_e32 v35, 0xffff0000, v78
	v_lshlrev_b32_e32 v36, 16, v79
	v_and_b32_e32 v37, 0xffff0000, v79
	v_pk_mul_f32 v[34:35], v[32:33], v[34:35] op_sel_hi:[0,1]
	v_pk_mul_f32 v[36:37], v[32:33], v[36:37] op_sel_hi:[0,1]
	v_pk_mul_f32 v[88:89], v[60:61], v[34:35]
	v_pk_mul_f32 v[90:91], v[62:63], v[36:37]
	global_store_dwordx4 v[30:31], v[88:91], off offset:16
	v_lshl_add_u64 v[30:31], v[12:13], 4, s[2:3]
	s_waitcnt vmcnt(6)
	v_lshlrev_b32_e32 v34, 16, v80
	v_and_b32_e32 v35, 0xffff0000, v80
	v_lshlrev_b32_e32 v36, 16, v81
	v_and_b32_e32 v37, 0xffff0000, v81
	v_pk_mul_f32 v[34:35], v[32:33], v[34:35] op_sel_hi:[0,1]
	v_pk_mul_f32 v[36:37], v[32:33], v[36:37] op_sel_hi:[0,1]
	v_pk_mul_f32 v[84:85], v[64:65], v[34:35]
	v_pk_mul_f32 v[86:87], v[66:67], v[36:37]
	global_store_dwordx4 v[30:31], v[84:87], off
	v_lshlrev_b32_e32 v34, 16, v82
	v_and_b32_e32 v35, 0xffff0000, v82
	v_lshlrev_b32_e32 v36, 16, v83
	v_and_b32_e32 v37, 0xffff0000, v83
	v_pk_mul_f32 v[34:35], v[32:33], v[34:35] op_sel_hi:[0,1]
	v_pk_mul_f32 v[36:37], v[32:33], v[36:37] op_sel_hi:[0,1]
	v_pk_mul_f32 v[88:89], v[68:69], v[34:35]
	v_pk_mul_f32 v[90:91], v[70:71], v[36:37]
	global_store_dwordx4 v[30:31], v[88:91], off offset:16
	s_cmpk_lt_i32 s6, 0x400
	s_cbranch_scc1 .LBB0_1419
